# mLSTM step 4: Q.C MFMA chain with 4-deep LDS fragment prefetch (was one exposed LDS round trip per MFMA)
# speedup vs baseline: 1.0082x; 1.0082x over previous
.LBB0_266:
	s_or_b64 exec, exec, s[12:13]
	s_add_u32 s12, s74, s4
	s_addc_u32 s13, s75, s31
	s_waitcnt lgkmcnt(0)
	v_lshl_add_u64 v[64:65], s[12:13], 0, v[96:97]
	v_add_co_u32_e32 v66, vcc, 0xf000000, v64
	s_waitcnt lgkmcnt(0)
	s_barrier
	v_lshrrev_b32_e32 v218, 5, v168
	s_nop 0
	v_addc_co_u32_e32 v67, vcc, 0, v65, vcc
	global_load_dwordx2 v[206:207], v[66:67], off sc1
	global_load_dwordx2 v[204:205], v[66:67], off offset:2048 sc1
	v_add_co_u32_e32 v66, vcc, 0xf001000, v64
	v_lshlrev_b32_e32 v217, 4, v218
	s_nop 0
	v_addc_co_u32_e32 v67, vcc, 0, v65, vcc
	global_load_dwordx2 v[202:203], v[66:67], off sc1
	global_load_dwordx2 v[200:201], v[66:67], off offset:2048 sc1
	v_add_co_u32_e32 v66, vcc, 0xf002000, v64
	v_add_u32_e32 v208, 0, v217
	s_nop 0
	v_addc_co_u32_e32 v67, vcc, 0, v65, vcc
	v_add_co_u32_e32 v64, vcc, 0xf003000, v64
	global_load_dwordx2 v[198:199], v[66:67], off sc1
	global_load_dwordx2 v[196:197], v[66:67], off offset:2048 sc1
	v_addc_co_u32_e32 v65, vcc, 0, v65, vcc
	global_load_dwordx2 v[194:195], v[64:65], off sc1
	global_load_dwordx2 v[192:193], v[64:65], off offset:2048 sc1
	v_lshlrev_b32_e32 v64, 4, v168
	global_load_dwordx4 v[152:155], v64, s[50:51]
	v_mov_b32_e32 v64, s10
	ds_read_b32 v96, v64
	v_or_b32_e32 v64, s11, v215
	v_lshlrev_b32_e32 v68, 3, v218
	v_mul_u32_u24_e32 v69, 0x110, v215
	v_mad_u64_u32 v[64:65], s[12:13], v64, s93, v[208:209]
	v_add3_u32 v176, 0, v68, v69
	ds_read_b128 v[168:171], v64 offset:53248
	ds_read_b128 v[164:167], v64 offset:53280
	ds_read_b128 v[160:163], v64 offset:53312
	ds_read_b128 v[156:159], v64 offset:53344
	v_add_u32_e32 v177, 0x2000, v176
	s_add_i32 s12, 0, 0x20b00
	v_add_u32_e32 v220, s12, v217
	v_add_u32_e32 v219, s15, v217
	s_add_i32 s13, 0, 0x20d00
	s_add_i32 s15, 0, 0x20e00
	s_add_i32 s42, 0, 0x20f00
	s_movk_i32 s43, 0x840
	v_or_b32_e32 v216, 32, v215
	ds_read2_b64 v[232:235], v176 offset0:0 offset1:2
	ds_read2_b64 v[236:239], v177 offset0:64 offset1:66
	ds_read2_b64 v[240:243], v176 offset0:4 offset1:6
	ds_read2_b64 v[180:183], v177 offset0:68 offset1:70
	v_cvt_pk_bf16_f32 v172, v0, v1
	v_cvt_pk_bf16_f32 v173, v2, v3
	v_cvt_pk_bf16_f32 v174, v4, v5
	v_cvt_pk_bf16_f32 v175, v6, v7
	s_nop 0
	s_waitcnt lgkmcnt(3)
	v_mfma_f32_32x32x16_bf16 v[80:95], v[232:235], v[172:175], 0
	ds_read2_b64 v[232:235], v176 offset0:8 offset1:10
	s_waitcnt lgkmcnt(3)
	v_mfma_f32_32x32x16_bf16 v[64:79], v[236:239], v[172:175], 0
	ds_read2_b64 v[236:239], v177 offset0:72 offset1:74
	v_cvt_pk_bf16_f32 v244, v8, v9
	v_cvt_pk_bf16_f32 v245, v10, v11
	v_cvt_pk_bf16_f32 v246, v12, v13
	v_cvt_pk_bf16_f32 v247, v14, v15
	v_pk_mul_f32 v[0:1], v[0:1], v[96:97] op_sel_hi:[1,0]
	v_pk_mul_f32 v[2:3], v[2:3], v[96:97] op_sel_hi:[1,0]
	v_pk_mul_f32 v[4:5], v[4:5], v[96:97] op_sel_hi:[1,0]
	v_pk_mul_f32 v[6:7], v[6:7], v[96:97] op_sel_hi:[1,0]
	s_waitcnt lgkmcnt(3)
	v_mfma_f32_32x32x16_bf16 v[80:95], v[240:243], v[244:247], v[80:95]
	ds_read2_b64 v[240:243], v176 offset0:12 offset1:14
	s_waitcnt lgkmcnt(3)
	v_mfma_f32_32x32x16_bf16 v[64:79], v[180:183], v[244:247], v[64:79]
	ds_read2_b64 v[180:183], v177 offset0:76 offset1:78
	v_cvt_pk_bf16_f32 v172, v16, v17
	v_cvt_pk_bf16_f32 v173, v18, v19
	v_cvt_pk_bf16_f32 v174, v20, v21
	v_cvt_pk_bf16_f32 v175, v22, v23
	v_pk_mul_f32 v[8:9], v[8:9], v[96:97] op_sel_hi:[1,0]
	v_pk_mul_f32 v[10:11], v[10:11], v[96:97] op_sel_hi:[1,0]
	v_pk_mul_f32 v[12:13], v[12:13], v[96:97] op_sel_hi:[1,0]
	v_pk_mul_f32 v[14:15], v[14:15], v[96:97] op_sel_hi:[1,0]
	s_waitcnt lgkmcnt(3)
	v_mfma_f32_32x32x16_bf16 v[80:95], v[232:235], v[172:175], v[80:95]
	ds_read2_b64 v[232:235], v176 offset0:16 offset1:18
	s_waitcnt lgkmcnt(3)
	v_mfma_f32_32x32x16_bf16 v[64:79], v[236:239], v[172:175], v[64:79]
	ds_read2_b64 v[236:239], v177 offset0:80 offset1:82
	v_cvt_pk_bf16_f32 v244, v24, v25
	v_cvt_pk_bf16_f32 v245, v26, v27
	v_cvt_pk_bf16_f32 v246, v28, v29
	v_cvt_pk_bf16_f32 v247, v30, v31
	v_pk_mul_f32 v[16:17], v[16:17], v[96:97] op_sel_hi:[1,0]
	v_pk_mul_f32 v[18:19], v[18:19], v[96:97] op_sel_hi:[1,0]
	v_pk_mul_f32 v[20:21], v[20:21], v[96:97] op_sel_hi:[1,0]
	v_pk_mul_f32 v[22:23], v[22:23], v[96:97] op_sel_hi:[1,0]
	s_waitcnt lgkmcnt(3)
	v_mfma_f32_32x32x16_bf16 v[80:95], v[240:243], v[244:247], v[80:95]
	ds_read2_b64 v[240:243], v176 offset0:20 offset1:22
	s_waitcnt lgkmcnt(3)
	v_mfma_f32_32x32x16_bf16 v[64:79], v[180:183], v[244:247], v[64:79]
	ds_read2_b64 v[180:183], v177 offset0:84 offset1:86
	v_cvt_pk_bf16_f32 v172, v32, v33
	v_cvt_pk_bf16_f32 v173, v34, v35
	v_cvt_pk_bf16_f32 v174, v36, v37
	v_cvt_pk_bf16_f32 v175, v38, v39
	v_pk_mul_f32 v[24:25], v[24:25], v[96:97] op_sel_hi:[1,0]
	v_pk_mul_f32 v[26:27], v[26:27], v[96:97] op_sel_hi:[1,0]
	v_pk_mul_f32 v[28:29], v[28:29], v[96:97] op_sel_hi:[1,0]
	v_pk_mul_f32 v[30:31], v[30:31], v[96:97] op_sel_hi:[1,0]
	s_waitcnt lgkmcnt(3)
	v_mfma_f32_32x32x16_bf16 v[80:95], v[232:235], v[172:175], v[80:95]
	ds_read2_b64 v[232:235], v176 offset0:24 offset1:26
	s_waitcnt lgkmcnt(3)
	v_mfma_f32_32x32x16_bf16 v[64:79], v[236:239], v[172:175], v[64:79]
	ds_read2_b64 v[236:239], v177 offset0:88 offset1:90
	v_cvt_pk_bf16_f32 v244, v40, v41
	v_cvt_pk_bf16_f32 v245, v42, v43
	v_cvt_pk_bf16_f32 v246, v44, v45
	v_cvt_pk_bf16_f32 v247, v46, v47
	v_pk_mul_f32 v[32:33], v[32:33], v[96:97] op_sel_hi:[1,0]
	v_pk_mul_f32 v[34:35], v[34:35], v[96:97] op_sel_hi:[1,0]
	v_pk_mul_f32 v[36:37], v[36:37], v[96:97] op_sel_hi:[1,0]
	v_pk_mul_f32 v[38:39], v[38:39], v[96:97] op_sel_hi:[1,0]
	s_waitcnt lgkmcnt(3)
	v_mfma_f32_32x32x16_bf16 v[80:95], v[240:243], v[244:247], v[80:95]
	ds_read2_b64 v[240:243], v176 offset0:28 offset1:30
	s_waitcnt lgkmcnt(3)
	v_mfma_f32_32x32x16_bf16 v[64:79], v[180:183], v[244:247], v[64:79]
	ds_read2_b64 v[180:183], v177 offset0:92 offset1:94
	v_cvt_pk_bf16_f32 v172, v48, v49
	v_cvt_pk_bf16_f32 v173, v50, v51
	v_cvt_pk_bf16_f32 v174, v52, v53
	v_cvt_pk_bf16_f32 v175, v54, v55
	v_pk_mul_f32 v[40:41], v[40:41], v[96:97] op_sel_hi:[1,0]
	v_pk_mul_f32 v[42:43], v[42:43], v[96:97] op_sel_hi:[1,0]
	v_pk_mul_f32 v[44:45], v[44:45], v[96:97] op_sel_hi:[1,0]
	v_pk_mul_f32 v[46:47], v[46:47], v[96:97] op_sel_hi:[1,0]
	s_waitcnt lgkmcnt(3)
	v_mfma_f32_32x32x16_bf16 v[80:95], v[232:235], v[172:175], v[80:95]
	s_waitcnt lgkmcnt(2)
	v_mfma_f32_32x32x16_bf16 v[64:79], v[236:239], v[172:175], v[64:79]
	v_cvt_pk_bf16_f32 v244, v56, v57
	v_cvt_pk_bf16_f32 v245, v58, v59
	v_cvt_pk_bf16_f32 v246, v60, v61
	v_cvt_pk_bf16_f32 v247, v62, v63
	v_pk_mul_f32 v[48:49], v[48:49], v[96:97] op_sel_hi:[1,0]
	v_pk_mul_f32 v[50:51], v[50:51], v[96:97] op_sel_hi:[1,0]
	v_pk_mul_f32 v[52:53], v[52:53], v[96:97] op_sel_hi:[1,0]
	v_pk_mul_f32 v[54:55], v[54:55], v[96:97] op_sel_hi:[1,0]
	s_waitcnt lgkmcnt(1)
	v_mfma_f32_32x32x16_bf16 v[80:95], v[240:243], v[244:247], v[80:95]
	v_pk_mul_f32 v[56:57], v[56:57], v[96:97] op_sel_hi:[1,0]
	v_pk_mul_f32 v[58:59], v[58:59], v[96:97] op_sel_hi:[1,0]
	v_pk_mul_f32 v[60:61], v[60:61], v[96:97] op_sel_hi:[1,0]
	v_pk_mul_f32 v[62:63], v[62:63], v[96:97] op_sel_hi:[1,0]
	v_lshl_add_u32 v176, v215, 1, s2
	v_mad_u32_u24 v177, v215, s93, v219
	s_waitcnt lgkmcnt(0)
	v_mfma_f32_32x32x16_bf16 v[64:79], v[180:183], v[244:247], v[64:79]
	ds_read_b128 v[172:175], v220
	ds_read_b128 v[232:235], v220 offset:32
	ds_read_b128 v[236:239], v220 offset:64
	ds_read_b128 v[240:243], v220 offset:96
	s_waitcnt lgkmcnt(3)
	v_pk_mul_f32 v[82:83], v[82:83], v[174:175]
	s_waitcnt lgkmcnt(2)
	v_pk_mul_f32 v[86:87], v[86:87], v[234:235]
	s_waitcnt lgkmcnt(1)
	v_pk_mul_f32 v[90:91], v[90:91], v[238:239]
	v_pk_mul_f32 v[88:89], v[88:89], v[236:237]
	v_pk_mul_f32 v[84:85], v[84:85], v[232:233]
	ds_read_b128 v[232:235], v177
	ds_read_b128 v[236:239], v177 offset:32
	s_waitcnt lgkmcnt(2)
	v_pk_mul_f32 v[94:95], v[94:95], v[242:243]
	v_pk_mul_f32 v[92:93], v[92:93], v[240:241]
	v_pk_mul_f32 v[80:81], v[80:81], v[172:173]
	s_waitcnt lgkmcnt(1)
	s_nop 0
	v_mfma_f32_32x32x16_bf16 v[80:95], v[232:235], v[168:171], v[80:95]
	ds_read_b128 v[232:235], v177 offset:64
	s_waitcnt lgkmcnt(1)
	v_mfma_f32_32x32x16_bf16 v[80:95], v[236:239], v[164:167], v[80:95]
	s_waitcnt lgkmcnt(0)
	v_mfma_f32_32x32x16_bf16 v[80:95], v[232:235], v[160:163], v[80:95]
	ds_read_b128 v[232:235], v177 offset:96
	v_add_u32_e32 v177, s13, v217
	s_waitcnt lgkmcnt(0)
	v_mfma_f32_32x32x16_bf16 v[80:95], v[232:235], v[156:159], v[80:95]
	ds_read_b128 v[232:235], v177
	v_add_u32_e32 v177, s15, v217
	ds_read_b128 v[236:239], v177
	v_add_u32_e32 v177, s42, v217
	ds_read_b128 v[240:243], v177
	s_waitcnt lgkmcnt(1)
	v_fma_f32 v172, v172, v232, v236
	v_fmac_f32_e32 v239, v175, v235
	s_waitcnt lgkmcnt(0)
	v_max_f32_e32 v177, v240, v240
	v_max_f32_e64 v172, |v172|, v177
	v_rcp_f32_e32 v172, v172
	s_nop 0
	v_mul_f32_e32 v80, v80, v172
	v_cvt_pk_bf16_f32 v172, v80, s0
	v_mad_u32_u24 v80, v218, s43, v176
	ds_write_b16 v80, v172
	v_fma_f32 v172, v173, v233, v237
	v_max_f32_e32 v173, v241, v241
	v_max_f32_e64 v172, |v172|, v173
	v_rcp_f32_e32 v172, v172
	s_nop 0
	v_mul_f32_e32 v81, v81, v172
	v_cvt_pk_bf16_f32 v81, v81, s0
	ds_write_b16 v80, v81 offset:528
	v_fma_f32 v81, v174, v234, v238
	v_max_f32_e32 v172, v242, v242
	v_max_f32_e64 v81, |v81|, v172
	v_rcp_f32_e32 v81, v81
	s_nop 0
	v_mul_f32_e32 v81, v82, v81
	v_cvt_pk_bf16_f32 v81, v81, s0
	ds_write_b16 v80, v81 offset:1056
	v_max_f32_e32 v81, v243, v243
	v_max_f32_e64 v81, |v239|, v81
	v_rcp_f32_e32 v81, v81
	s_nop 0
	v_mul_f32_e32 v81, v83, v81
	v_cvt_pk_bf16_f32 v81, v81, s0
	ds_write_b16 v80, v81 offset:1584
	v_lshl_or_b32 v81, v218, 2, 8
	v_lshlrev_b32_e32 v82, 2, v81
	v_add_u32_e32 v83, s12, v82
	ds_read_b128 v[172:175], v83
	v_add_u32_e32 v83, s13, v82
	ds_read_b128 v[232:235], v83
	v_add_u32_e32 v83, s15, v82
	v_add_u32_e32 v82, s42, v82
	ds_read_b128 v[236:239], v83
	ds_read_b128 v[240:243], v82
	v_mad_u32_u24 v81, v81, s85, v176
	s_waitcnt lgkmcnt(1)
	v_fma_f32 v82, v172, v232, v236
	s_waitcnt lgkmcnt(0)
	v_max_f32_e32 v83, v240, v240
	v_max_f32_e64 v82, |v82|, v83
	v_rcp_f32_e32 v82, v82
	v_max_f32_e32 v83, v241, v241
	v_fmac_f32_e32 v239, v175, v235
	v_mul_f32_e32 v82, v84, v82
	v_cvt_pk_bf16_f32 v82, v82, s0
	ds_write_b16 v81, v82
	v_fma_f32 v82, v173, v233, v237
	v_max_f32_e64 v82, |v82|, v83
	v_rcp_f32_e32 v82, v82
	v_max_f32_e32 v83, v242, v242
	v_mul_f32_e32 v82, v85, v82
	v_cvt_pk_bf16_f32 v82, v82, s0
	ds_write_b16 v80, v82 offset:4752
	v_fma_f32 v82, v174, v234, v238
	v_max_f32_e64 v82, |v82|, v83
	v_rcp_f32_e32 v82, v82
	s_nop 0
	v_mul_f32_e32 v82, v86, v82
	v_cvt_pk_bf16_f32 v82, v82, s0
	ds_write_b16 v80, v82 offset:5280
	v_max_f32_e32 v82, v243, v243
	v_max_f32_e64 v82, |v239|, v82
	v_rcp_f32_e32 v82, v82
	v_or_b32_e32 v86, 64, v217
	v_mul_f32_e32 v82, v87, v82
	v_cvt_pk_bf16_f32 v82, v82, s0
	ds_write_b16 v80, v82 offset:5808
	v_add_u32_e32 v87, s13, v86
	v_add_u32_e32 v82, s12, v86
	ds_read_b128 v[172:175], v87
	v_add_u32_e32 v87, s15, v86
	v_add_u32_e32 v86, s42, v86
	ds_read_b128 v[82:85], v82
	ds_read_b128 v[236:239], v86
	ds_read_b128 v[232:235], v87
	s_waitcnt lgkmcnt(1)
	v_max_f32_e32 v86, v236, v236
	s_waitcnt lgkmcnt(0)
	v_fma_f32 v82, v82, v172, v232
	v_max_f32_e64 v82, |v82|, v86
	v_rcp_f32_e32 v82, v82
	v_fmac_f32_e32 v235, v85, v175
	v_mul_f32_e32 v82, v88, v82
	v_cvt_pk_bf16_f32 v82, v82, s0
	ds_write_b16 v81, v82 offset:4224
	v_fma_f32 v82, v83, v173, v233
	v_max_f32_e32 v83, v237, v237
	v_max_f32_e64 v82, |v82|, v83
	v_rcp_f32_e32 v82, v82
	v_max_f32_e32 v83, v238, v238
	v_mul_f32_e32 v82, v89, v82
	v_cvt_pk_bf16_f32 v82, v82, s0
	ds_write_b16 v80, v82 offset:8976
	v_fma_f32 v82, v84, v174, v234
	v_max_f32_e64 v82, |v82|, v83
	v_rcp_f32_e32 v82, v82
	s_nop 0
	v_mul_f32_e32 v82, v90, v82
	v_cvt_pk_bf16_f32 v82, v82, s0
	ds_write_b16 v80, v82 offset:9504
	v_max_f32_e32 v82, v239, v239
	v_max_f32_e64 v82, |v235|, v82
	v_rcp_f32_e32 v82, v82
	v_or_b32_e32 v90, 0x60, v217
	v_add_u32_e32 v86, s13, v90
	v_mul_f32_e32 v82, v91, v82
	v_cvt_pk_bf16_f32 v82, v82, s0
	ds_write_b16 v80, v82 offset:10032
	v_add_u32_e32 v82, s12, v90
	v_add_u32_e32 v91, s15, v90
	v_add_u32_e32 v90, s42, v90
	ds_read_b128 v[82:85], v82
	ds_read_b128 v[86:89], v86
	ds_read_b128 v[172:175], v91
	ds_read_b128 v[232:235], v90
	s_waitcnt lgkmcnt(1)
	v_fma_f32 v82, v82, v86, v172
	s_waitcnt lgkmcnt(0)
	v_max_f32_e32 v86, v232, v232
	v_max_f32_e64 v82, |v82|, v86
	v_rcp_f32_e32 v82, v82
	v_fmac_f32_e32 v175, v85, v89
	v_mul_f32_e32 v82, v92, v82
	v_cvt_pk_bf16_f32 v82, v82, s0
	ds_write_b16 v81, v82 offset:8448
	v_fma_f32 v82, v83, v87, v173
	v_max_f32_e32 v83, v233, v233
	v_max_f32_e64 v82, |v82|, v83
	v_rcp_f32_e32 v82, v82
	v_max_f32_e32 v83, v234, v234
	v_mul_f32_e32 v82, v93, v82
	v_cvt_pk_bf16_f32 v82, v82, s0
	ds_write_b16 v80, v82 offset:13200
	v_fma_f32 v82, v84, v88, v174
	v_max_f32_e64 v82, |v82|, v83
	v_rcp_f32_e32 v82, v82
	s_nop 0
	v_mul_f32_e32 v82, v94, v82
	v_cvt_pk_bf16_f32 v82, v82, s0
	ds_write_b16 v80, v82 offset:13728
	v_max_f32_e32 v82, v235, v235
	v_max_f32_e64 v82, |v175|, v82
	v_rcp_f32_e32 v82, v82
	v_mad_u32_u24 v94, v216, s93, v219
	v_mul_f32_e32 v82, v95, v82
	v_cvt_pk_bf16_f32 v82, v82, s0
	ds_write_b16 v80, v82 offset:14256
	ds_read_b128 v[82:85], v220 offset:128
	ds_read_b128 v[86:89], v220 offset:160
	ds_read_b128 v[90:93], v220 offset:192
	ds_read_b128 v[172:175], v220 offset:224
	s_waitcnt lgkmcnt(3)
	v_pk_mul_f32 v[66:67], v[66:67], v[84:85]
	s_waitcnt lgkmcnt(2)
	v_pk_mul_f32 v[68:69], v[68:69], v[86:87]
	s_waitcnt lgkmcnt(1)
	v_pk_mul_f32 v[72:73], v[72:73], v[90:91]
	v_pk_mul_f32 v[74:75], v[74:75], v[92:93]
	v_pk_mul_f32 v[70:71], v[70:71], v[88:89]
	ds_read_b128 v[86:89], v94
	ds_read_b128 v[90:93], v94 offset:32
	s_waitcnt lgkmcnt(2)
	v_pk_mul_f32 v[76:77], v[76:77], v[172:173]
	v_pk_mul_f32 v[78:79], v[78:79], v[174:175]
	v_pk_mul_f32 v[64:65], v[64:65], v[82:83]
	s_waitcnt lgkmcnt(1)
	s_nop 0
	v_mfma_f32_32x32x16_bf16 v[64:79], v[86:89], v[168:171], v[64:79]
	ds_read_b128 v[86:89], v94 offset:64
	s_waitcnt lgkmcnt(1)
	v_mfma_f32_32x32x16_bf16 v[64:79], v[90:93], v[164:167], v[64:79]
	s_waitcnt lgkmcnt(0)
	v_mfma_f32_32x32x16_bf16 v[64:79], v[86:89], v[160:163], v[64:79]
	ds_read_b128 v[86:89], v94 offset:96
	v_or_b32_e32 v94, 0x80, v217
	v_add_u32_e32 v90, s15, v94
	ds_read_b128 v[90:93], v90
	s_waitcnt lgkmcnt(1)
	v_mfma_f32_32x32x16_bf16 v[64:79], v[86:89], v[156:159], v[64:79]
	v_add_u32_e32 v86, s13, v94
	v_add_u32_e32 v94, s42, v94
	ds_read_b128 v[86:89], v86
	ds_read_b128 v[172:175], v94
	s_waitcnt lgkmcnt(1)
	v_fma_f32 v82, v82, v86, v90
	s_waitcnt lgkmcnt(0)
	v_max_f32_e32 v86, v172, v172
	v_max_f32_e64 v82, |v82|, v86
	v_rcp_f32_e32 v82, v82
	v_fmac_f32_e32 v93, v85, v89
	v_or_b32_e32 v90, 0xa0, v217
	v_add_u32_e32 v86, s15, v90
	v_mul_f32_e32 v64, v64, v82
	v_cvt_pk_bf16_f32 v64, v64, s0
	ds_write_b16 v81, v64 offset:12672
	v_fma_f32 v64, v83, v87, v91
	v_max_f32_e32 v82, v173, v173
	v_max_f32_e64 v64, |v64|, v82
	v_rcp_f32_e32 v64, v64
	v_add_u32_e32 v82, s13, v90
	v_mul_f32_e32 v64, v65, v64
	v_cvt_pk_bf16_f32 v64, v64, s0
	ds_write_b16 v80, v64 offset:17424
	v_fma_f32 v64, v84, v88, v92
	v_max_f32_e32 v65, v174, v174
	v_max_f32_e64 v64, |v64|, v65
	v_rcp_f32_e32 v64, v64
	s_nop 0
	v_mul_f32_e32 v64, v66, v64
	v_cvt_pk_bf16_f32 v64, v64, s0
	ds_write_b16 v80, v64 offset:17952
	v_max_f32_e32 v64, v175, v175
	v_max_f32_e64 v64, |v93|, v64
	v_rcp_f32_e32 v64, v64
	s_nop 0
	v_mul_f32_e32 v64, v67, v64
	v_cvt_pk_bf16_f32 v64, v64, s0
	ds_write_b16 v80, v64 offset:18480
	v_add_u32_e32 v64, s12, v90
	v_add_u32_e32 v90, s42, v90
	ds_read_b128 v[64:67], v64
	ds_read_b128 v[82:85], v82
	ds_read_b128 v[86:89], v86
	ds_read_b128 v[90:93], v90
	s_waitcnt lgkmcnt(1)
	v_fma_f32 v64, v64, v82, v86
	s_waitcnt lgkmcnt(0)
	v_max_f32_e32 v82, v90, v90
	v_max_f32_e64 v64, |v64|, v82
	v_rcp_f32_e32 v64, v64
	v_fmac_f32_e32 v89, v67, v85
	v_or_b32_e32 v86, 0xc0, v217
	v_add_u32_e32 v82, s15, v86
	v_mul_f32_e32 v64, v68, v64
	v_cvt_pk_bf16_f32 v64, v64, s0
	ds_write_b16 v81, v64 offset:16896
	v_fma_f32 v64, v65, v83, v87
	v_max_f32_e32 v65, v91, v91
	v_max_f32_e64 v64, |v64|, v65
	v_rcp_f32_e32 v64, v64
	v_max_f32_e32 v65, v92, v92
	v_add_u32_e32 v68, s13, v86
	v_mul_f32_e32 v64, v69, v64
	v_cvt_pk_bf16_f32 v64, v64, s0
	ds_write_b16 v80, v64 offset:21648
	v_fma_f32 v64, v66, v84, v88
	v_max_f32_e64 v64, |v64|, v65
	v_rcp_f32_e32 v64, v64
	s_nop 0
	v_mul_f32_e32 v64, v70, v64
	v_cvt_pk_bf16_f32 v64, v64, s0
	ds_write_b16 v80, v64 offset:22176
	v_max_f32_e32 v64, v93, v93
	v_max_f32_e64 v64, |v89|, v64
	v_rcp_f32_e32 v64, v64
	s_nop 0
	v_mul_f32_e32 v64, v71, v64
	v_cvt_pk_bf16_f32 v64, v64, s0
	ds_write_b16 v80, v64 offset:22704
	v_add_u32_e32 v64, s12, v86
	v_add_u32_e32 v86, s42, v86
	ds_read_b128 v[64:67], v64
	ds_read_b128 v[68:71], v68
	ds_read_b128 v[82:85], v82
	ds_read_b128 v[86:89], v86
	s_waitcnt lgkmcnt(1)
	v_fma_f32 v64, v64, v68, v82
	s_waitcnt lgkmcnt(0)
	v_max_f32_e32 v68, v86, v86
	v_max_f32_e64 v64, |v64|, v68
	v_rcp_f32_e32 v64, v64
	v_fmac_f32_e32 v85, v67, v71
	v_or_b32_e32 v82, 0xe0, v217
	v_add_u32_e32 v68, s13, v82
	v_mul_f32_e32 v64, v72, v64
	v_cvt_pk_bf16_f32 v64, v64, s0
	ds_write_b16 v81, v64 offset:21120
	v_fma_f32 v64, v65, v69, v83
	v_max_f32_e32 v65, v87, v87
	v_max_f32_e64 v64, |v64|, v65
	v_rcp_f32_e32 v64, v64
	v_max_f32_e32 v65, v88, v88
	v_add_u32_e32 v72, s15, v82
	v_mul_f32_e32 v64, v73, v64
	v_cvt_pk_bf16_f32 v64, v64, s0
	ds_write_b16 v80, v64 offset:25872
	v_fma_f32 v64, v66, v70, v84
	v_max_f32_e64 v64, |v64|, v65
	v_rcp_f32_e32 v64, v64
	s_nop 0
	v_mul_f32_e32 v64, v74, v64
	v_cvt_pk_bf16_f32 v64, v64, s0
	ds_write_b16 v80, v64 offset:26400
	v_max_f32_e32 v64, v89, v89
	v_max_f32_e64 v64, |v85|, v64
	v_rcp_f32_e32 v64, v64
	s_nop 0
	v_mul_f32_e32 v64, v75, v64
	v_cvt_pk_bf16_f32 v64, v64, s0
	ds_write_b16 v80, v64 offset:26928
	v_add_u32_e32 v64, s12, v82
	v_add_u32_e32 v82, s42, v82
	ds_read_b128 v[64:67], v64
	ds_read_b128 v[68:71], v68
	ds_read_b128 v[72:75], v72
	ds_read_b128 v[82:85], v82
	s_waitcnt lgkmcnt(1)
	v_fma_f32 v64, v64, v68, v72
	s_waitcnt lgkmcnt(0)
	v_max_f32_e32 v68, v82, v82
	v_max_f32_e64 v64, |v64|, v68
	v_rcp_f32_e32 v64, v64
	v_fmac_f32_e32 v75, v67, v71
	v_mad_u32_u24 v72, v215, s93, v208
	v_mul_f32_e32 v64, v76, v64
	v_cvt_pk_bf16_f32 v64, v64, s0
	ds_write_b16 v81, v64 offset:25344
	v_fma_f32 v64, v65, v69, v73
	v_max_f32_e32 v65, v83, v83
	v_max_f32_e64 v64, |v64|, v65
	v_rcp_f32_e32 v64, v64
	v_max_f32_e32 v65, v84, v84
	v_mad_u32_u24 v73, v216, s93, v208
	v_mul_f32_e32 v64, v77, v64
	v_cvt_pk_bf16_f32 v64, v64, s0
	ds_write_b16 v80, v64 offset:30096
	v_fma_f32 v64, v66, v70, v74
	v_max_f32_e64 v64, |v64|, v65
	v_rcp_f32_e32 v64, v64
	v_and_b32_e32 v74, 3, v214
	v_cmp_eq_u32_e32 vcc, 0, v74
	v_mul_f32_e32 v64, v78, v64
	v_cvt_pk_bf16_f32 v64, v64, s0
	ds_write_b16 v80, v64 offset:30624
	v_max_f32_e32 v64, v85, v85
	v_max_f32_e64 v64, |v75|, v64
	v_rcp_f32_e32 v64, v64
	s_nop 0
	v_mul_f32_e32 v64, v79, v64
	v_cvt_pk_bf16_f32 v64, v64, s0
	ds_write_b16 v80, v64 offset:31152
	ds_read_b128 v[64:67], v72 offset:34816
	ds_read_b128 v[68:71], v72 offset:34848
	ds_read_b128 v[76:79], v72 offset:34880
	ds_read_b128 v[80:83], v72 offset:34912
	ds_read_b128 v[84:87], v73 offset:34816
	ds_read_b128 v[88:91], v73 offset:34848
	s_waitcnt lgkmcnt(5)
	v_mfma_f32_32x32x16_bf16 v[0:15], v[64:67], v[168:171], v[0:15]
	ds_read_b128 v[64:67], v73 offset:34880
	s_waitcnt lgkmcnt(5)
	v_mfma_f32_32x32x16_bf16 v[0:15], v[68:71], v[164:167], v[0:15]
	ds_read_b128 v[68:71], v73 offset:34912
	s_waitcnt lgkmcnt(5)
	v_mfma_f32_32x32x16_bf16 v[0:15], v[76:79], v[160:163], v[0:15]
	ds_read_b128 v[76:79], v72 offset:44032
	s_waitcnt lgkmcnt(5)
	v_mfma_f32_32x32x16_bf16 v[0:15], v[80:83], v[156:159], v[0:15]
	ds_read_b128 v[80:83], v72 offset:44064
	s_waitcnt lgkmcnt(5)
	v_mfma_f32_32x32x16_bf16 v[16:31], v[84:87], v[168:171], v[16:31]
	ds_read_b128 v[84:87], v72 offset:44096
	s_waitcnt lgkmcnt(5)
	v_mfma_f32_32x32x16_bf16 v[16:31], v[88:91], v[164:167], v[16:31]
	ds_read_b128 v[88:91], v72 offset:44128
	s_waitcnt lgkmcnt(5)
	v_mfma_f32_32x32x16_bf16 v[16:31], v[64:67], v[160:163], v[16:31]
	ds_read_b128 v[64:67], v72 offset:48640
	s_waitcnt lgkmcnt(5)
	v_mfma_f32_32x32x16_bf16 v[16:31], v[68:71], v[156:159], v[16:31]
	ds_read_b128 v[68:71], v72 offset:48672
	s_waitcnt lgkmcnt(5)
	v_mfma_f32_32x32x16_bf16 v[32:47], v[76:79], v[168:171], v[32:47]
	ds_read_b128 v[76:79], v72 offset:48704
	s_waitcnt lgkmcnt(5)
	v_mfma_f32_32x32x16_bf16 v[32:47], v[80:83], v[164:167], v[32:47]
	ds_read_b128 v[80:83], v72 offset:48736
	s_waitcnt lgkmcnt(5)
	v_mfma_f32_32x32x16_bf16 v[32:47], v[84:87], v[160:163], v[32:47]
	s_waitcnt lgkmcnt(4)
	v_mfma_f32_32x32x16_bf16 v[32:47], v[88:91], v[156:159], v[32:47]
	s_waitcnt lgkmcnt(3)
	v_mfma_f32_32x32x16_bf16 v[48:63], v[64:67], v[168:171], v[48:63]
	s_waitcnt lgkmcnt(2)
	v_mfma_f32_32x32x16_bf16 v[48:63], v[68:71], v[164:167], v[48:63]
	s_waitcnt lgkmcnt(1)
	v_mfma_f32_32x32x16_bf16 v[48:63], v[76:79], v[160:163], v[48:63]
	s_waitcnt lgkmcnt(0)
	v_mfma_f32_32x32x16_bf16 v[48:63], v[80:83], v[156:159], v[48:63]
	v_ashrrev_i32_e32 v64, 2, v214
	v_mul_lo_u32 v65, v64, s93
	v_lshlrev_b32_e32 v66, 5, v74
	v_add3_u32 v65, 0, v65, v66
	ds_read_b128 v[66:69], v65 offset:34816
	ds_read_b128 v[70:73], v65 offset:34832
	s_waitcnt lgkmcnt(1)
	v_lshlrev_b32_e32 v65, 16, v66
	v_and_b32_e32 v66, 0xffff0000, v66
	v_add_f32_e32 v65, v65, v66
	s_waitcnt lgkmcnt(0)
	v_lshlrev_b32_e32 v66, 16, v70
	v_and_b32_e32 v70, 0xffff0000, v70
	v_add_f32_e32 v66, v66, v70
	v_add_f32_e32 v65, v65, v66
	v_lshlrev_b32_e32 v66, 16, v67
	v_and_b32_e32 v67, 0xffff0000, v67
	v_add_f32_e32 v66, v66, v67
	v_lshlrev_b32_e32 v67, 16, v71
	v_and_b32_e32 v70, 0xffff0000, v71
	v_add_f32_e32 v67, v67, v70
	v_add_f32_e32 v65, 0, v65
	v_add_f32_e32 v66, v66, v67
	v_add_f32_e32 v65, v66, v65
	v_lshlrev_b32_e32 v66, 16, v68
	v_and_b32_e32 v67, 0xffff0000, v68
	v_add_f32_e32 v66, v66, v67
	v_lshlrev_b32_e32 v67, 16, v72
	v_and_b32_e32 v68, 0xffff0000, v72
	v_add_f32_e32 v67, v67, v68
	v_add_f32_e32 v66, v66, v67
	v_add_f32_e32 v65, v66, v65
	v_lshlrev_b32_e32 v66, 16, v69
	v_and_b32_e32 v67, 0xffff0000, v69
	v_add_f32_e32 v66, v66, v67
	v_lshlrev_b32_e32 v67, 16, v73
	v_and_b32_e32 v68, 0xffff0000, v73
	v_add_f32_e32 v67, v67, v68
	v_add_f32_e32 v66, v66, v67
	v_add_f32_e32 v65, v66, v65
	ds_bpermute_b32 v66, v189, v65
	s_waitcnt lgkmcnt(0)
	v_add_f32_e32 v65, v65, v66
	ds_bpermute_b32 v66, v191, v65
	s_and_saveexec_b64 s[12:13], vcc
	s_cbranch_execz .LBB0_206
	v_lshl_add_u32 v64, v64, 2, 0
	v_add_u32_e32 v64, 0x21000, v64
	s_waitcnt lgkmcnt(0)
	v_add_f32_e32 v65, v65, v66
	ds_read_b32 v66, v64
	s_waitcnt lgkmcnt(0)
	v_fmac_f32_e32 v65, v96, v66
	ds_write_b32 v64, v65
	s_branch .LBB0_206
